# fix phase: column-stationary mapping (conv weights loaded once per thread, all rows' edge loads in flight together)
# baseline (speedup 1.0000x reference)
; __device__ __forceinline__ int otid(int wv) { int t; asm volatile("v_mbcnt_lo_u32_b32 %0, -1, 0\n\tv_mbcnt_hi_u32_b32 %0, -1, %0\n\tv_lshl_add_u32 %0, %1, 6, %0" : "=&v"(t) : "s"(wv)); return t; }
; __device__ void fix_phase(int wv, const Params& p, int li) {
;     const float* edge = (const float*)(p.ws + WS_EDGE); const float* cw = (const float*)(p.ws + WS_CW) + (size_t)li * 4 * NUP; bf16_t* act = (bf16_t*)(p.ws + WS_ACT);
;     const int total = 1024 * (FFD / 4);
;     const int tid = otid(wv);
;     for (int idx = blockIdx.x * NTHR + tid; idx < total; idx += gridDim.x * NTHR) {
;         const int e = idx / (FFD / 4), c = (idx % (FFD / 4)) * 4; const int band = e >> 1, hi = e & 1; const int R = band * 64 + (hi ? 63 : 0);
;         const int ca = (c >> 7) * 256 + (c & 127), cg_ = ca + 128;
;         const bool seqstart = (R == 0 || R == 8192 || R == 16384), seqend = (R == 8191 || R == 16383 || R == 32767);
;         const float* ep = edge + (size_t)band * 4 * NUP;
;         f32x4 pa, pg, ua, ug, na, ng; const f32x4 zero = {0, 0, 0, 0};
;         if (!hi) { pa = seqstart ? zero : *(const f32x4*)(ep - NUP + ca); pg = seqstart ? zero : *(const f32x4*)(ep - NUP + cg_);
;             ua = *(const f32x4*)(ep + ca); ug = *(const f32x4*)(ep + cg_); na = *(const f32x4*)(ep + NUP + ca); ng = *(const f32x4*)(ep + NUP + cg_); }
;         else { pa = *(const f32x4*)(ep + 2 * NUP + ca); pg = *(const f32x4*)(ep + 2 * NUP + cg_); ua = *(const f32x4*)(ep + 3 * NUP + ca); ug = *(const f32x4*)(ep + 3 * NUP + cg_);
;             na = seqend ? zero : *(const f32x4*)(ep + 4 * NUP + ca); ng = seqend ? zero : *(const f32x4*)(ep + 4 * NUP + cg_); }
;         const f32x4 a = *(const f32x4*)(cw + ca) * pa + *(const f32x4*)(cw + NUP + ca) * ua + *(const f32x4*)(cw + 2 * NUP + ca) * na + *(const f32x4*)(cw + 3 * NUP + ca);
;         const f32x4 g = *(const f32x4*)(cw + cg_) * pg + *(const f32x4*)(cw + NUP + cg_) * ug + *(const f32x4*)(cw + 2 * NUP + cg_) * ng + *(const f32x4*)(cw + 3 * NUP + cg_);
.LBB0_559:
	s_or_b64 exec, exec, s[0:1]
	v_readlane_b32 s0, v253, 0
	s_waitcnt lgkmcnt(0)
	s_barrier
	v_mbcnt_lo_u32_b32 v1, -1, 0
	v_mbcnt_hi_u32_b32 v1, -1, v1
	v_lshl_add_u32 v1, s33, 6, v1
	s_nop 0
	v_add_u32_e32 v36, s0, v1
	s_mov_b32 s0, 0xb0000
	v_cmp_gt_i32_e32 vcc, s0, v36
	s_and_saveexec_b64 s[4:5], vcc
	s_cbranch_execz .LBB0_592
	v_lshrrev_b32_e32 v5, 6, v36
	v_mov_b32_e32 v14, 0xba2e8ba3
	v_mul_hi_u32 v2, v5, v14
	v_lshrrev_b32_e32 v2, 3, v2
	v_mul_u32_u24_e32 v5, 0x2c0, v2
	v_sub_u32_e32 v3, v36, v5
	v_lshrrev_b32_e32 v5, 5, v3
	v_and_b32_e32 v6, 31, v3
	v_lshlrev_b32_e32 v6, 2, v6
	v_lshl_add_u32 v5, v5, 8, v6
	v_lshlrev_b32_e32 v4, 2, v5
	global_load_dwordx4 v[208:211], v4, s[92:93]
	global_load_dwordx4 v[212:215], v4, s[92:93] offset:512
	global_load_dwordx4 v[216:219], v4, s[96:97]
	global_load_dwordx4 v[220:223], v4, s[96:97] offset:512
	global_load_dwordx4 v[224:227], v4, s[20:21]
	global_load_dwordx4 v[228:231], v4, s[20:21] offset:512
	global_load_dwordx4 v[232:235], v4, s[84:85]
	global_load_dwordx4 v[236:239], v4, s[84:85] offset:512
	v_add_u32_e32 v67, 0, v2
	v_min_u32_e32 v7, 0x3ff, v67
	v_lshrrev_b32_e32 v8, 1, v7
	v_and_b32_e32 v9, 1, v7
	v_cmp_eq_u32_e64 s[8:9], 1, v9
	v_cmp_eq_u32_e64 s[10:11], 0, v8
	s_movk_i32 s36, 0x80
	v_cmp_eq_u32_e64 s[12:13], s36, v8
	s_movk_i32 s36, 0x100
	v_cmp_eq_u32_e64 s[14:15], s36, v8
	s_or_b64 s[10:11], s[10:11], s[12:13]
	s_or_b64 s[10:11], s[10:11], s[14:15]
	v_cndmask_b32_e64 v5, 1, 0, s[10:11]
	v_or_b32_e32 v5, v5, v9
	s_movk_i32 s36, 0x7f
	v_cmp_eq_u32_e64 s[10:11], s36, v8
	s_movk_i32 s36, 0xff
	v_cmp_eq_u32_e64 s[12:13], s36, v8
	s_movk_i32 s36, 0x1ff
	v_cmp_eq_u32_e64 s[14:15], s36, v8
	s_or_b64 s[10:11], s[10:11], s[12:13]
	s_or_b64 s[10:11], s[10:11], s[14:15]
	v_cndmask_b32_e64 v6, 1, 0, s[10:11]
	v_xor_b32_e32 v7, 1, v9
	v_or_b32_e32 v6, v6, v7
	v_cvt_f32_u32_e32 v64, v5
	v_cvt_f32_u32_e32 v65, v6
	v_sub_u32_e32 v7, 0, v5
	v_cndmask_b32_e64 v10, v7, 2, s[8:9]
	v_mul_u32_u24_e32 v11, 3, v9
	v_add_u32_e32 v7, 3, v6
	v_cndmask_b32_e64 v12, 1, v7, s[8:9]
	v_lshlrev_b32_e32 v7, 2, v8
	v_add_u32_e32 v5, v7, v10
	v_mul_u32_u24_e32 v5, 0x5800, v5
	v_add_u32_e32 v13, v5, v4
	global_load_dwordx4 v[40:43], v13, s[40:41]
	global_load_dwordx4 v[44:47], v13, s[40:41] offset:512
	v_add_u32_e32 v5, v7, v11
	v_mul_u32_u24_e32 v5, 0x5800, v5
	v_add_u32_e32 v13, v5, v4
	global_load_dwordx4 v[48:51], v13, s[40:41]
	global_load_dwordx4 v[52:55], v13, s[40:41] offset:512
	v_add_u32_e32 v5, v7, v12
	v_mul_u32_u24_e32 v5, 0x5800, v5
	v_add_u32_e32 v13, v5, v4
	global_load_dwordx4 v[56:59], v13, s[40:41]
	global_load_dwordx4 v[60:63], v13, s[40:41] offset:512
	v_mul_u32_u24_e32 v5, 63, v9
	v_lshl_add_u32 v5, v8, 6, v5
	v_mul_u32_u24_e32 v66, 0x1600, v5
	v_lshl_add_u32 v66, v3, 3, v66
	v_add_u32_e32 v95, 186, v2
	v_min_u32_e32 v7, 0x3ff, v95
	v_lshrrev_b32_e32 v8, 1, v7
	v_and_b32_e32 v9, 1, v7
	v_cmp_eq_u32_e64 s[8:9], 1, v9
	v_cmp_eq_u32_e64 s[10:11], 0, v8
	s_movk_i32 s36, 0x80
	v_cmp_eq_u32_e64 s[12:13], s36, v8
	s_movk_i32 s36, 0x100
	v_cmp_eq_u32_e64 s[14:15], s36, v8
	s_or_b64 s[10:11], s[10:11], s[12:13]
	s_or_b64 s[10:11], s[10:11], s[14:15]
	v_cndmask_b32_e64 v5, 1, 0, s[10:11]
	v_or_b32_e32 v5, v5, v9
	s_movk_i32 s36, 0x7f
	v_cmp_eq_u32_e64 s[10:11], s36, v8
	s_movk_i32 s36, 0xff
	v_cmp_eq_u32_e64 s[12:13], s36, v8
	s_movk_i32 s36, 0x1ff
	v_cmp_eq_u32_e64 s[14:15], s36, v8
	s_or_b64 s[10:11], s[10:11], s[12:13]
	s_or_b64 s[10:11], s[10:11], s[14:15]
	v_cndmask_b32_e64 v6, 1, 0, s[10:11]
	v_xor_b32_e32 v7, 1, v9
	v_or_b32_e32 v6, v6, v7
	v_cvt_f32_u32_e32 v92, v5
	v_cvt_f32_u32_e32 v93, v6
	v_sub_u32_e32 v7, 0, v5
	v_cndmask_b32_e64 v10, v7, 2, s[8:9]
	v_mul_u32_u24_e32 v11, 3, v9
	v_add_u32_e32 v7, 3, v6
	v_cndmask_b32_e64 v12, 1, v7, s[8:9]
	v_lshlrev_b32_e32 v7, 2, v8
	v_add_u32_e32 v5, v7, v10
	v_mul_u32_u24_e32 v5, 0x5800, v5
	v_add_u32_e32 v13, v5, v4
	global_load_dwordx4 v[68:71], v13, s[40:41]
	global_load_dwordx4 v[72:75], v13, s[40:41] offset:512
	v_add_u32_e32 v5, v7, v11
	v_mul_u32_u24_e32 v5, 0x5800, v5
	v_add_u32_e32 v13, v5, v4
	global_load_dwordx4 v[76:79], v13, s[40:41]
	global_load_dwordx4 v[80:83], v13, s[40:41] offset:512
	v_add_u32_e32 v5, v7, v12
	v_mul_u32_u24_e32 v5, 0x5800, v5
	v_add_u32_e32 v13, v5, v4
	global_load_dwordx4 v[84:87], v13, s[40:41]
	global_load_dwordx4 v[88:91], v13, s[40:41] offset:512
	v_mul_u32_u24_e32 v5, 63, v9
	v_lshl_add_u32 v5, v8, 6, v5
	v_mul_u32_u24_e32 v94, 0x1600, v5
	v_lshl_add_u32 v94, v3, 3, v94
	v_add_u32_e32 v123, 372, v2
	v_min_u32_e32 v7, 0x3ff, v123
	v_lshrrev_b32_e32 v8, 1, v7
	v_and_b32_e32 v9, 1, v7
	v_cmp_eq_u32_e64 s[8:9], 1, v9
	v_cmp_eq_u32_e64 s[10:11], 0, v8
	s_movk_i32 s36, 0x80
	v_cmp_eq_u32_e64 s[12:13], s36, v8
	s_movk_i32 s36, 0x100
	v_cmp_eq_u32_e64 s[14:15], s36, v8
	s_or_b64 s[10:11], s[10:11], s[12:13]
	s_or_b64 s[10:11], s[10:11], s[14:15]
	v_cndmask_b32_e64 v5, 1, 0, s[10:11]
	v_or_b32_e32 v5, v5, v9
	s_movk_i32 s36, 0x7f
	v_cmp_eq_u32_e64 s[10:11], s36, v8
	s_movk_i32 s36, 0xff
	v_cmp_eq_u32_e64 s[12:13], s36, v8
	s_movk_i32 s36, 0x1ff
	v_cmp_eq_u32_e64 s[14:15], s36, v8
	s_or_b64 s[10:11], s[10:11], s[12:13]
	s_or_b64 s[10:11], s[10:11], s[14:15]
	v_cndmask_b32_e64 v6, 1, 0, s[10:11]
	v_xor_b32_e32 v7, 1, v9
	v_or_b32_e32 v6, v6, v7
	v_cvt_f32_u32_e32 v120, v5
	v_cvt_f32_u32_e32 v121, v6
	v_sub_u32_e32 v7, 0, v5
	v_cndmask_b32_e64 v10, v7, 2, s[8:9]
	v_mul_u32_u24_e32 v11, 3, v9
	v_add_u32_e32 v7, 3, v6
	v_cndmask_b32_e64 v12, 1, v7, s[8:9]
	v_lshlrev_b32_e32 v7, 2, v8
	v_add_u32_e32 v5, v7, v10
	v_mul_u32_u24_e32 v5, 0x5800, v5
	v_add_u32_e32 v13, v5, v4
	global_load_dwordx4 v[96:99], v13, s[40:41]
; __device__ void fix_phase(int wv, const Params& p, int li) {
;     ...
;         const int e = idx / (FFD / 4), c = (idx % (FFD / 4)) * 4; const int band = e >> 1, hi = e & 1; const int R = band * 64 + (hi ? 63 : 0);
;         const int ca = (c >> 7) * 256 + (c & 127), cg_ = ca + 128;
;         const bool seqstart = (R == 0 || R == 8192 || R == 16384), seqend = (R == 8191 || R == 16383 || R == 32767);
;         const float* ep = edge + (size_t)band * 4 * NUP;
;         f32x4 pa, pg, ua, ug, na, ng; const f32x4 zero = {0, 0, 0, 0};
;         if (!hi) { pa = seqstart ? zero : *(const f32x4*)(ep - NUP + ca); pg = seqstart ? zero : *(const f32x4*)(ep - NUP + cg_);
;             ua = *(const f32x4*)(ep + ca); ug = *(const f32x4*)(ep + cg_); na = *(const f32x4*)(ep + NUP + ca); ng = *(const f32x4*)(ep + NUP + cg_); }
;         else { pa = *(const f32x4*)(ep + 2 * NUP + ca); pg = *(const f32x4*)(ep + 2 * NUP + cg_); ua = *(const f32x4*)(ep + 3 * NUP + ca); ug = *(const f32x4*)(ep + 3 * NUP + cg_);
;             na = seqend ? zero : *(const f32x4*)(ep + 4 * NUP + ca); ng = seqend ? zero : *(const f32x4*)(ep + 4 * NUP + cg_); }
	global_load_dwordx4 v[100:103], v13, s[40:41] offset:512
	v_add_u32_e32 v5, v7, v11
	v_mul_u32_u24_e32 v5, 0x5800, v5
	v_add_u32_e32 v13, v5, v4
	global_load_dwordx4 v[104:107], v13, s[40:41]
	global_load_dwordx4 v[108:111], v13, s[40:41] offset:512
	v_add_u32_e32 v5, v7, v12
	v_mul_u32_u24_e32 v5, 0x5800, v5
	v_add_u32_e32 v13, v5, v4
	global_load_dwordx4 v[112:115], v13, s[40:41]
	global_load_dwordx4 v[116:119], v13, s[40:41] offset:512
	v_mul_u32_u24_e32 v5, 63, v9
	v_lshl_add_u32 v5, v8, 6, v5
	v_mul_u32_u24_e32 v122, 0x1600, v5
	v_lshl_add_u32 v122, v3, 3, v122
	v_add_u32_e32 v151, 558, v2
	v_min_u32_e32 v7, 0x3ff, v151
	v_lshrrev_b32_e32 v8, 1, v7
	v_and_b32_e32 v9, 1, v7
	v_cmp_eq_u32_e64 s[8:9], 1, v9
	v_cmp_eq_u32_e64 s[10:11], 0, v8
	s_movk_i32 s36, 0x80
	v_cmp_eq_u32_e64 s[12:13], s36, v8
	s_movk_i32 s36, 0x100
	v_cmp_eq_u32_e64 s[14:15], s36, v8
	s_or_b64 s[10:11], s[10:11], s[12:13]
	s_or_b64 s[10:11], s[10:11], s[14:15]
	v_cndmask_b32_e64 v5, 1, 0, s[10:11]
	v_or_b32_e32 v5, v5, v9
	s_movk_i32 s36, 0x7f
	v_cmp_eq_u32_e64 s[10:11], s36, v8
	s_movk_i32 s36, 0xff
	v_cmp_eq_u32_e64 s[12:13], s36, v8
	s_movk_i32 s36, 0x1ff
	v_cmp_eq_u32_e64 s[14:15], s36, v8
	s_or_b64 s[10:11], s[10:11], s[12:13]
	s_or_b64 s[10:11], s[10:11], s[14:15]
	v_cndmask_b32_e64 v6, 1, 0, s[10:11]
	v_xor_b32_e32 v7, 1, v9
	v_or_b32_e32 v6, v6, v7
	v_cvt_f32_u32_e32 v148, v5
	v_cvt_f32_u32_e32 v149, v6
	v_sub_u32_e32 v7, 0, v5
	v_cndmask_b32_e64 v10, v7, 2, s[8:9]
	v_mul_u32_u24_e32 v11, 3, v9
	v_add_u32_e32 v7, 3, v6
	v_cndmask_b32_e64 v12, 1, v7, s[8:9]
	v_lshlrev_b32_e32 v7, 2, v8
	v_add_u32_e32 v5, v7, v10
	v_mul_u32_u24_e32 v5, 0x5800, v5
	v_add_u32_e32 v13, v5, v4
	global_load_dwordx4 v[124:127], v13, s[40:41]
	global_load_dwordx4 v[128:131], v13, s[40:41] offset:512
	v_add_u32_e32 v5, v7, v11
	v_mul_u32_u24_e32 v5, 0x5800, v5
	v_add_u32_e32 v13, v5, v4
	global_load_dwordx4 v[132:135], v13, s[40:41]
	global_load_dwordx4 v[136:139], v13, s[40:41] offset:512
	v_add_u32_e32 v5, v7, v12
	v_mul_u32_u24_e32 v5, 0x5800, v5
	v_add_u32_e32 v13, v5, v4
	global_load_dwordx4 v[140:143], v13, s[40:41]
	global_load_dwordx4 v[144:147], v13, s[40:41] offset:512
	v_mul_u32_u24_e32 v5, 63, v9
	v_lshl_add_u32 v5, v8, 6, v5
	v_mul_u32_u24_e32 v150, 0x1600, v5
	v_lshl_add_u32 v150, v3, 3, v150
	v_add_u32_e32 v179, 744, v2
	v_min_u32_e32 v7, 0x3ff, v179
	v_lshrrev_b32_e32 v8, 1, v7
	v_and_b32_e32 v9, 1, v7
	v_cmp_eq_u32_e64 s[8:9], 1, v9
	v_cmp_eq_u32_e64 s[10:11], 0, v8
	s_movk_i32 s36, 0x80
	v_cmp_eq_u32_e64 s[12:13], s36, v8
	s_movk_i32 s36, 0x100
	v_cmp_eq_u32_e64 s[14:15], s36, v8
	s_or_b64 s[10:11], s[10:11], s[12:13]
	s_or_b64 s[10:11], s[10:11], s[14:15]
	v_cndmask_b32_e64 v5, 1, 0, s[10:11]
	v_or_b32_e32 v5, v5, v9
	s_movk_i32 s36, 0x7f
	v_cmp_eq_u32_e64 s[10:11], s36, v8
	s_movk_i32 s36, 0xff
	v_cmp_eq_u32_e64 s[12:13], s36, v8
	s_movk_i32 s36, 0x1ff
	v_cmp_eq_u32_e64 s[14:15], s36, v8
	s_or_b64 s[10:11], s[10:11], s[12:13]
	s_or_b64 s[10:11], s[10:11], s[14:15]
	v_cndmask_b32_e64 v6, 1, 0, s[10:11]
	v_xor_b32_e32 v7, 1, v9
	v_or_b32_e32 v6, v6, v7
	v_cvt_f32_u32_e32 v176, v5
	v_cvt_f32_u32_e32 v177, v6
	v_sub_u32_e32 v7, 0, v5
	v_cndmask_b32_e64 v10, v7, 2, s[8:9]
	v_mul_u32_u24_e32 v11, 3, v9
	v_add_u32_e32 v7, 3, v6
	v_cndmask_b32_e64 v12, 1, v7, s[8:9]
	v_lshlrev_b32_e32 v7, 2, v8
	v_add_u32_e32 v5, v7, v10
	v_mul_u32_u24_e32 v5, 0x5800, v5
	v_add_u32_e32 v13, v5, v4
	global_load_dwordx4 v[152:155], v13, s[40:41]
	global_load_dwordx4 v[156:159], v13, s[40:41] offset:512
	v_add_u32_e32 v5, v7, v11
	v_mul_u32_u24_e32 v5, 0x5800, v5
	v_add_u32_e32 v13, v5, v4
	global_load_dwordx4 v[160:163], v13, s[40:41]
	global_load_dwordx4 v[164:167], v13, s[40:41] offset:512
	v_add_u32_e32 v5, v7, v12
	v_mul_u32_u24_e32 v5, 0x5800, v5
	v_add_u32_e32 v13, v5, v4
	global_load_dwordx4 v[168:171], v13, s[40:41]
	global_load_dwordx4 v[172:175], v13, s[40:41] offset:512
	v_mul_u32_u24_e32 v5, 63, v9
	v_lshl_add_u32 v5, v8, 6, v5
	v_mul_u32_u24_e32 v178, 0x1600, v5
	v_lshl_add_u32 v178, v3, 3, v178
	v_add_u32_e32 v207, 930, v2
	v_min_u32_e32 v7, 0x3ff, v207
	v_lshrrev_b32_e32 v8, 1, v7
	v_and_b32_e32 v9, 1, v7
	v_cmp_eq_u32_e64 s[8:9], 1, v9
	v_cmp_eq_u32_e64 s[10:11], 0, v8
	s_movk_i32 s36, 0x80
	v_cmp_eq_u32_e64 s[12:13], s36, v8
	s_movk_i32 s36, 0x100
	v_cmp_eq_u32_e64 s[14:15], s36, v8
	s_or_b64 s[10:11], s[10:11], s[12:13]
	s_or_b64 s[10:11], s[10:11], s[14:15]
	v_cndmask_b32_e64 v5, 1, 0, s[10:11]
	v_or_b32_e32 v5, v5, v9
	s_movk_i32 s36, 0x7f
	v_cmp_eq_u32_e64 s[10:11], s36, v8
	s_movk_i32 s36, 0xff
	v_cmp_eq_u32_e64 s[12:13], s36, v8
	s_movk_i32 s36, 0x1ff
	v_cmp_eq_u32_e64 s[14:15], s36, v8
	s_or_b64 s[10:11], s[10:11], s[12:13]
	s_or_b64 s[10:11], s[10:11], s[14:15]
	v_cndmask_b32_e64 v6, 1, 0, s[10:11]
	v_xor_b32_e32 v7, 1, v9
	v_or_b32_e32 v6, v6, v7
	v_cvt_f32_u32_e32 v204, v5
	v_cvt_f32_u32_e32 v205, v6
	v_sub_u32_e32 v7, 0, v5
	v_cndmask_b32_e64 v10, v7, 2, s[8:9]
	v_mul_u32_u24_e32 v11, 3, v9
	v_add_u32_e32 v7, 3, v6
	v_cndmask_b32_e64 v12, 1, v7, s[8:9]
	v_lshlrev_b32_e32 v7, 2, v8
	v_add_u32_e32 v5, v7, v10
	v_mul_u32_u24_e32 v5, 0x5800, v5
	v_add_u32_e32 v13, v5, v4
	global_load_dwordx4 v[180:183], v13, s[40:41]
	global_load_dwordx4 v[184:187], v13, s[40:41] offset:512
	v_add_u32_e32 v5, v7, v11
	v_mul_u32_u24_e32 v5, 0x5800, v5
	v_add_u32_e32 v13, v5, v4
	global_load_dwordx4 v[188:191], v13, s[40:41]
	global_load_dwordx4 v[192:195], v13, s[40:41] offset:512
	v_add_u32_e32 v5, v7, v12
	v_mul_u32_u24_e32 v5, 0x5800, v5
	v_add_u32_e32 v13, v5, v4
	global_load_dwordx4 v[196:199], v13, s[40:41]
	global_load_dwordx4 v[200:203], v13, s[40:41] offset:512
	v_mul_u32_u24_e32 v5, 63, v9
	v_lshl_add_u32 v5, v8, 6, v5
	v_mul_u32_u24_e32 v206, 0x1600, v5
	v_lshl_add_u32 v206, v3, 3, v206
	s_mov_b64 s[6:7], exec
	s_movk_i32 s36, 186
	v_cmp_gt_u32_e32 vcc, s36, v2
	s_and_b64 s[6:7], s[6:7], vcc
	s_waitcnt vmcnt(30)
; __device__ __forceinline__ unsigned cvt_pk_bf16(float lo, float hi) { const f2_t v = {lo, hi}; const bf2_t b = __builtin_convertvector(v, bf2_t); return __builtin_bit_cast(unsigned, b); }
; __device__ void fix_phase(int wv, const Params& p, int li) {
;     ...
;         const f32x4 a = *(const f32x4*)(cw + ca) * pa + *(const f32x4*)(cw + NUP + ca) * ua + *(const f32x4*)(cw + 2 * NUP + ca) * na + *(const f32x4*)(cw + 3 * NUP + ca);
;         const f32x4 g = *(const f32x4*)(cw + cg_) * pg + *(const f32x4*)(cw + NUP + cg_) * ug + *(const f32x4*)(cw + 2 * NUP + cg_) * ng + *(const f32x4*)(cw + 3 * NUP + cg_);
;         float o[4];
; #pragma unroll
;         for (int j = 0; j < 4; ++j) o[j] = a[j] * g[j] / (1.0f + __expf(-g[j]));
;         u32x2 wv; wv.x = cvt_pk_bf16(o[0], o[1]); wv.y = cvt_pk_bf16(o[2], o[3]);
;         *(u32x2*)(act + (size_t)R * FFD + c) = wv;
	v_pk_mul_f32 v[40:41], v[40:41], v[64:65] op_sel_hi:[1,0]
	v_pk_mul_f32 v[42:43], v[42:43], v[64:65] op_sel_hi:[1,0]
	v_pk_mul_f32 v[44:45], v[44:45], v[64:65] op_sel_hi:[1,0]
	v_pk_mul_f32 v[46:47], v[46:47], v[64:65] op_sel_hi:[1,0]
	v_pk_mul_f32 v[56:57], v[56:57], v[64:65] op_sel:[0,1] op_sel_hi:[1,1]
	v_pk_mul_f32 v[58:59], v[58:59], v[64:65] op_sel:[0,1] op_sel_hi:[1,1]
	v_pk_mul_f32 v[60:61], v[60:61], v[64:65] op_sel:[0,1] op_sel_hi:[1,1]
	v_pk_mul_f32 v[62:63], v[62:63], v[64:65] op_sel:[0,1] op_sel_hi:[1,1]
	v_pk_mul_f32 v[40:41], v[208:209], v[40:41]
	v_pk_mul_f32 v[42:43], v[210:211], v[42:43]
	v_pk_mul_f32 v[44:45], v[212:213], v[44:45]
	v_pk_mul_f32 v[46:47], v[214:215], v[46:47]
	v_pk_fma_f32 v[40:41], v[216:217], v[48:49], v[40:41]
	v_pk_fma_f32 v[42:43], v[218:219], v[50:51], v[42:43]
	v_pk_fma_f32 v[44:45], v[220:221], v[52:53], v[44:45]
	v_pk_fma_f32 v[46:47], v[222:223], v[54:55], v[46:47]
	v_pk_fma_f32 v[40:41], v[224:225], v[56:57], v[40:41]
	v_pk_fma_f32 v[42:43], v[226:227], v[58:59], v[42:43]
	v_pk_fma_f32 v[44:45], v[228:229], v[60:61], v[44:45]
	v_pk_fma_f32 v[46:47], v[230:231], v[62:63], v[46:47]
	v_pk_add_f32 v[40:41], v[40:41], v[232:233]
	v_pk_add_f32 v[42:43], v[42:43], v[234:235]
	v_pk_add_f32 v[44:45], v[44:45], v[236:237]
	v_pk_add_f32 v[46:47], v[46:47], v[238:239]
	v_mul_f32_e32 v52, 0xbfb8aa3b, v44
	v_mul_f32_e32 v53, 0xbfb8aa3b, v45
	v_mul_f32_e32 v54, 0xbfb8aa3b, v46
	v_mul_f32_e32 v55, 0xbfb8aa3b, v47
	v_exp_f32_e32 v52, v52
	v_exp_f32_e32 v53, v53
	v_exp_f32_e32 v54, v54
	v_exp_f32_e32 v55, v55
	v_add_f32_e32 v52, 1.0, v52
	v_add_f32_e32 v53, 1.0, v53
	v_add_f32_e32 v54, 1.0, v54
	v_add_f32_e32 v55, 1.0, v55
	v_rcp_f32_e32 v52, v52
	v_rcp_f32_e32 v53, v53
	v_rcp_f32_e32 v54, v54
	v_rcp_f32_e32 v55, v55
	s_nop 0
	v_pk_mul_f32 v[44:45], v[44:45], v[52:53]
	v_pk_mul_f32 v[46:47], v[46:47], v[54:55]
	s_nop 0
	v_pk_mul_f32 v[40:41], v[40:41], v[44:45]
	v_pk_mul_f32 v[42:43], v[42:43], v[46:47]
	s_nop 0
	v_cvt_pk_bf16_f32 v48, v40, v41
	v_cvt_pk_bf16_f32 v49, v42, v43
	s_movk_i32 s36, 0x400
	v_cmp_gt_u32_e32 vcc, s36, v67
	s_and_b64 exec, s[6:7], vcc
	global_store_dwordx2 v66, v[48:49], s[76:77]
	s_mov_b64 exec, -1
	s_waitcnt vmcnt(25)
	v_pk_mul_f32 v[68:69], v[68:69], v[92:93] op_sel_hi:[1,0]
	v_pk_mul_f32 v[70:71], v[70:71], v[92:93] op_sel_hi:[1,0]
	v_pk_mul_f32 v[72:73], v[72:73], v[92:93] op_sel_hi:[1,0]
	v_pk_mul_f32 v[74:75], v[74:75], v[92:93] op_sel_hi:[1,0]
	v_pk_mul_f32 v[84:85], v[84:85], v[92:93] op_sel:[0,1] op_sel_hi:[1,1]
	v_pk_mul_f32 v[86:87], v[86:87], v[92:93] op_sel:[0,1] op_sel_hi:[1,1]
	v_pk_mul_f32 v[88:89], v[88:89], v[92:93] op_sel:[0,1] op_sel_hi:[1,1]
	v_pk_mul_f32 v[90:91], v[90:91], v[92:93] op_sel:[0,1] op_sel_hi:[1,1]
	v_pk_mul_f32 v[68:69], v[208:209], v[68:69]
	v_pk_mul_f32 v[70:71], v[210:211], v[70:71]
	v_pk_mul_f32 v[72:73], v[212:213], v[72:73]
	v_pk_mul_f32 v[74:75], v[214:215], v[74:75]
	v_pk_fma_f32 v[68:69], v[216:217], v[76:77], v[68:69]
	v_pk_fma_f32 v[70:71], v[218:219], v[78:79], v[70:71]
	v_pk_fma_f32 v[72:73], v[220:221], v[80:81], v[72:73]
	v_pk_fma_f32 v[74:75], v[222:223], v[82:83], v[74:75]
	v_pk_fma_f32 v[68:69], v[224:225], v[84:85], v[68:69]
	v_pk_fma_f32 v[70:71], v[226:227], v[86:87], v[70:71]
	v_pk_fma_f32 v[72:73], v[228:229], v[88:89], v[72:73]
	v_pk_fma_f32 v[74:75], v[230:231], v[90:91], v[74:75]
	v_pk_add_f32 v[68:69], v[68:69], v[232:233]
	v_pk_add_f32 v[70:71], v[70:71], v[234:235]
	v_pk_add_f32 v[72:73], v[72:73], v[236:237]
	v_pk_add_f32 v[74:75], v[74:75], v[238:239]
	v_mul_f32_e32 v80, 0xbfb8aa3b, v72
	v_mul_f32_e32 v81, 0xbfb8aa3b, v73
	v_mul_f32_e32 v82, 0xbfb8aa3b, v74
	v_mul_f32_e32 v83, 0xbfb8aa3b, v75
	v_exp_f32_e32 v80, v80
	v_exp_f32_e32 v81, v81
	v_exp_f32_e32 v82, v82
	v_exp_f32_e32 v83, v83
	v_add_f32_e32 v80, 1.0, v80
	v_add_f32_e32 v81, 1.0, v81
	v_add_f32_e32 v82, 1.0, v82
	v_add_f32_e32 v83, 1.0, v83
	v_rcp_f32_e32 v80, v80
	v_rcp_f32_e32 v81, v81
	v_rcp_f32_e32 v82, v82
	v_rcp_f32_e32 v83, v83
	s_nop 0
	v_pk_mul_f32 v[72:73], v[72:73], v[80:81]
	v_pk_mul_f32 v[74:75], v[74:75], v[82:83]
	s_nop 0
	v_pk_mul_f32 v[68:69], v[68:69], v[72:73]
	v_pk_mul_f32 v[70:71], v[70:71], v[74:75]
	s_nop 0
	v_cvt_pk_bf16_f32 v76, v68, v69
	v_cvt_pk_bf16_f32 v77, v70, v71
	s_movk_i32 s36, 0x400
	v_cmp_gt_u32_e32 vcc, s36, v95
	s_and_b64 exec, s[6:7], vcc
	global_store_dwordx2 v94, v[76:77], s[76:77]
	s_mov_b64 exec, -1
	s_waitcnt vmcnt(20)
	v_pk_mul_f32 v[96:97], v[96:97], v[120:121] op_sel_hi:[1,0]
	v_pk_mul_f32 v[98:99], v[98:99], v[120:121] op_sel_hi:[1,0]
	v_pk_mul_f32 v[100:101], v[100:101], v[120:121] op_sel_hi:[1,0]
	v_pk_mul_f32 v[102:103], v[102:103], v[120:121] op_sel_hi:[1,0]
	v_pk_mul_f32 v[112:113], v[112:113], v[120:121] op_sel:[0,1] op_sel_hi:[1,1]
	v_pk_mul_f32 v[114:115], v[114:115], v[120:121] op_sel:[0,1] op_sel_hi:[1,1]
	v_pk_mul_f32 v[116:117], v[116:117], v[120:121] op_sel:[0,1] op_sel_hi:[1,1]
	v_pk_mul_f32 v[118:119], v[118:119], v[120:121] op_sel:[0,1] op_sel_hi:[1,1]
	v_pk_mul_f32 v[96:97], v[208:209], v[96:97]
	v_pk_mul_f32 v[98:99], v[210:211], v[98:99]
	v_pk_mul_f32 v[100:101], v[212:213], v[100:101]
	v_pk_mul_f32 v[102:103], v[214:215], v[102:103]
	v_pk_fma_f32 v[96:97], v[216:217], v[104:105], v[96:97]
	v_pk_fma_f32 v[98:99], v[218:219], v[106:107], v[98:99]
	v_pk_fma_f32 v[100:101], v[220:221], v[108:109], v[100:101]
	v_pk_fma_f32 v[102:103], v[222:223], v[110:111], v[102:103]
	v_pk_fma_f32 v[96:97], v[224:225], v[112:113], v[96:97]
	v_pk_fma_f32 v[98:99], v[226:227], v[114:115], v[98:99]
	v_pk_fma_f32 v[100:101], v[228:229], v[116:117], v[100:101]
	v_pk_fma_f32 v[102:103], v[230:231], v[118:119], v[102:103]
	v_pk_add_f32 v[96:97], v[96:97], v[232:233]
	v_pk_add_f32 v[98:99], v[98:99], v[234:235]
	v_pk_add_f32 v[100:101], v[100:101], v[236:237]
	v_pk_add_f32 v[102:103], v[102:103], v[238:239]
	v_mul_f32_e32 v108, 0xbfb8aa3b, v100
	v_mul_f32_e32 v109, 0xbfb8aa3b, v101
	v_mul_f32_e32 v110, 0xbfb8aa3b, v102
	v_mul_f32_e32 v111, 0xbfb8aa3b, v103
	v_exp_f32_e32 v108, v108
	v_exp_f32_e32 v109, v109
	v_exp_f32_e32 v110, v110
	v_exp_f32_e32 v111, v111
	v_add_f32_e32 v108, 1.0, v108
	v_add_f32_e32 v109, 1.0, v109
	v_add_f32_e32 v110, 1.0, v110
	v_add_f32_e32 v111, 1.0, v111
	v_rcp_f32_e32 v108, v108
	v_rcp_f32_e32 v109, v109
	v_rcp_f32_e32 v110, v110
	v_rcp_f32_e32 v111, v111
	s_nop 0
	v_pk_mul_f32 v[100:101], v[100:101], v[108:109]
	v_pk_mul_f32 v[102:103], v[102:103], v[110:111]
	s_nop 0
	v_pk_mul_f32 v[96:97], v[96:97], v[100:101]
	v_pk_mul_f32 v[98:99], v[98:99], v[102:103]
	s_nop 0
	v_cvt_pk_bf16_f32 v104, v96, v97
	v_cvt_pk_bf16_f32 v105, v98, v99
	s_movk_i32 s36, 0x400
	v_cmp_gt_u32_e32 vcc, s36, v123
	s_and_b64 exec, s[6:7], vcc
	global_store_dwordx2 v122, v[104:105], s[76:77]
	s_mov_b64 exec, -1
	s_waitcnt vmcnt(15)
; __device__ __forceinline__ unsigned cvt_pk_bf16(float lo, float hi) { const f2_t v = {lo, hi}; const bf2_t b = __builtin_convertvector(v, bf2_t); return __builtin_bit_cast(unsigned, b); }
; __device__ void fix_phase(int wv, const Params& p, int li) {
;     ...
;         const f32x4 a = *(const f32x4*)(cw + ca) * pa + *(const f32x4*)(cw + NUP + ca) * ua + *(const f32x4*)(cw + 2 * NUP + ca) * na + *(const f32x4*)(cw + 3 * NUP + ca);
;         const f32x4 g = *(const f32x4*)(cw + cg_) * pg + *(const f32x4*)(cw + NUP + cg_) * ug + *(const f32x4*)(cw + 2 * NUP + cg_) * ng + *(const f32x4*)(cw + 3 * NUP + cg_);
;         float o[4];
; #pragma unroll
;         for (int j = 0; j < 4; ++j) o[j] = a[j] * g[j] / (1.0f + __expf(-g[j]));
;         u32x2 wv; wv.x = cvt_pk_bf16(o[0], o[1]); wv.y = cvt_pk_bf16(o[2], o[3]);
;         *(u32x2*)(act + (size_t)R * FFD + c) = wv;
	v_pk_mul_f32 v[124:125], v[124:125], v[148:149] op_sel_hi:[1,0]
	v_pk_mul_f32 v[126:127], v[126:127], v[148:149] op_sel_hi:[1,0]
	v_pk_mul_f32 v[128:129], v[128:129], v[148:149] op_sel_hi:[1,0]
	v_pk_mul_f32 v[130:131], v[130:131], v[148:149] op_sel_hi:[1,0]
	v_pk_mul_f32 v[140:141], v[140:141], v[148:149] op_sel:[0,1] op_sel_hi:[1,1]
	v_pk_mul_f32 v[142:143], v[142:143], v[148:149] op_sel:[0,1] op_sel_hi:[1,1]
	v_pk_mul_f32 v[144:145], v[144:145], v[148:149] op_sel:[0,1] op_sel_hi:[1,1]
	v_pk_mul_f32 v[146:147], v[146:147], v[148:149] op_sel:[0,1] op_sel_hi:[1,1]
	v_pk_mul_f32 v[124:125], v[208:209], v[124:125]
	v_pk_mul_f32 v[126:127], v[210:211], v[126:127]
	v_pk_mul_f32 v[128:129], v[212:213], v[128:129]
	v_pk_mul_f32 v[130:131], v[214:215], v[130:131]
	v_pk_fma_f32 v[124:125], v[216:217], v[132:133], v[124:125]
	v_pk_fma_f32 v[126:127], v[218:219], v[134:135], v[126:127]
	v_pk_fma_f32 v[128:129], v[220:221], v[136:137], v[128:129]
	v_pk_fma_f32 v[130:131], v[222:223], v[138:139], v[130:131]
	v_pk_fma_f32 v[124:125], v[224:225], v[140:141], v[124:125]
	v_pk_fma_f32 v[126:127], v[226:227], v[142:143], v[126:127]
	v_pk_fma_f32 v[128:129], v[228:229], v[144:145], v[128:129]
	v_pk_fma_f32 v[130:131], v[230:231], v[146:147], v[130:131]
	v_pk_add_f32 v[124:125], v[124:125], v[232:233]
	v_pk_add_f32 v[126:127], v[126:127], v[234:235]
	v_pk_add_f32 v[128:129], v[128:129], v[236:237]
	v_pk_add_f32 v[130:131], v[130:131], v[238:239]
	v_mul_f32_e32 v136, 0xbfb8aa3b, v128
	v_mul_f32_e32 v137, 0xbfb8aa3b, v129
	v_mul_f32_e32 v138, 0xbfb8aa3b, v130
	v_mul_f32_e32 v139, 0xbfb8aa3b, v131
	v_exp_f32_e32 v136, v136
	v_exp_f32_e32 v137, v137
	v_exp_f32_e32 v138, v138
	v_exp_f32_e32 v139, v139
	v_add_f32_e32 v136, 1.0, v136
	v_add_f32_e32 v137, 1.0, v137
	v_add_f32_e32 v138, 1.0, v138
	v_add_f32_e32 v139, 1.0, v139
	v_rcp_f32_e32 v136, v136
	v_rcp_f32_e32 v137, v137
	v_rcp_f32_e32 v138, v138
	v_rcp_f32_e32 v139, v139
	s_nop 0
	v_pk_mul_f32 v[128:129], v[128:129], v[136:137]
	v_pk_mul_f32 v[130:131], v[130:131], v[138:139]
	s_nop 0
	v_pk_mul_f32 v[124:125], v[124:125], v[128:129]
	v_pk_mul_f32 v[126:127], v[126:127], v[130:131]
	s_nop 0
	v_cvt_pk_bf16_f32 v132, v124, v125
	v_cvt_pk_bf16_f32 v133, v126, v127
	s_movk_i32 s36, 0x400
	v_cmp_gt_u32_e32 vcc, s36, v151
	s_and_b64 exec, s[6:7], vcc
	global_store_dwordx2 v150, v[132:133], s[76:77]
	s_mov_b64 exec, -1
	s_waitcnt vmcnt(10)
; __device__ __forceinline__ unsigned cvt_pk_bf16(float lo, float hi) { const f2_t v = {lo, hi}; const bf2_t b = __builtin_convertvector(v, bf2_t); return __builtin_bit_cast(unsigned, b); }
; __device__ void fix_phase(int wv, const Params& p, int li) {
;     ...
;         const f32x4 a = *(const f32x4*)(cw + ca) * pa + *(const f32x4*)(cw + NUP + ca) * ua + *(const f32x4*)(cw + 2 * NUP + ca) * na + *(const f32x4*)(cw + 3 * NUP + ca);
;         const f32x4 g = *(const f32x4*)(cw + cg_) * pg + *(const f32x4*)(cw + NUP + cg_) * ug + *(const f32x4*)(cw + 2 * NUP + cg_) * ng + *(const f32x4*)(cw + 3 * NUP + cg_);
;         float o[4];
; #pragma unroll
;         for (int j = 0; j < 4; ++j) o[j] = a[j] * g[j] / (1.0f + __expf(-g[j]));
;         u32x2 wv; wv.x = cvt_pk_bf16(o[0], o[1]); wv.y = cvt_pk_bf16(o[2], o[3]);
;         *(u32x2*)(act + (size_t)R * FFD + c) = wv;
	v_pk_mul_f32 v[152:153], v[152:153], v[176:177] op_sel_hi:[1,0]
	v_pk_mul_f32 v[154:155], v[154:155], v[176:177] op_sel_hi:[1,0]
	v_pk_mul_f32 v[156:157], v[156:157], v[176:177] op_sel_hi:[1,0]
	v_pk_mul_f32 v[158:159], v[158:159], v[176:177] op_sel_hi:[1,0]
	v_pk_mul_f32 v[168:169], v[168:169], v[176:177] op_sel:[0,1] op_sel_hi:[1,1]
	v_pk_mul_f32 v[170:171], v[170:171], v[176:177] op_sel:[0,1] op_sel_hi:[1,1]
	v_pk_mul_f32 v[172:173], v[172:173], v[176:177] op_sel:[0,1] op_sel_hi:[1,1]
	v_pk_mul_f32 v[174:175], v[174:175], v[176:177] op_sel:[0,1] op_sel_hi:[1,1]
	v_pk_mul_f32 v[152:153], v[208:209], v[152:153]
	v_pk_mul_f32 v[154:155], v[210:211], v[154:155]
	v_pk_mul_f32 v[156:157], v[212:213], v[156:157]
	v_pk_mul_f32 v[158:159], v[214:215], v[158:159]
	v_pk_fma_f32 v[152:153], v[216:217], v[160:161], v[152:153]
	v_pk_fma_f32 v[154:155], v[218:219], v[162:163], v[154:155]
	v_pk_fma_f32 v[156:157], v[220:221], v[164:165], v[156:157]
	v_pk_fma_f32 v[158:159], v[222:223], v[166:167], v[158:159]
	v_pk_fma_f32 v[152:153], v[224:225], v[168:169], v[152:153]
	v_pk_fma_f32 v[154:155], v[226:227], v[170:171], v[154:155]
	v_pk_fma_f32 v[156:157], v[228:229], v[172:173], v[156:157]
	v_pk_fma_f32 v[158:159], v[230:231], v[174:175], v[158:159]
	v_pk_add_f32 v[152:153], v[152:153], v[232:233]
	v_pk_add_f32 v[154:155], v[154:155], v[234:235]
	v_pk_add_f32 v[156:157], v[156:157], v[236:237]
	v_pk_add_f32 v[158:159], v[158:159], v[238:239]
	v_mul_f32_e32 v164, 0xbfb8aa3b, v156
	v_mul_f32_e32 v165, 0xbfb8aa3b, v157
	v_mul_f32_e32 v166, 0xbfb8aa3b, v158
	v_mul_f32_e32 v167, 0xbfb8aa3b, v159
	v_exp_f32_e32 v164, v164
	v_exp_f32_e32 v165, v165
	v_exp_f32_e32 v166, v166
	v_exp_f32_e32 v167, v167
	v_add_f32_e32 v164, 1.0, v164
	v_add_f32_e32 v165, 1.0, v165
	v_add_f32_e32 v166, 1.0, v166
	v_add_f32_e32 v167, 1.0, v167
	v_rcp_f32_e32 v164, v164
	v_rcp_f32_e32 v165, v165
	v_rcp_f32_e32 v166, v166
	v_rcp_f32_e32 v167, v167
	s_nop 0
	v_pk_mul_f32 v[156:157], v[156:157], v[164:165]
	v_pk_mul_f32 v[158:159], v[158:159], v[166:167]
	s_nop 0
	v_pk_mul_f32 v[152:153], v[152:153], v[156:157]
	v_pk_mul_f32 v[154:155], v[154:155], v[158:159]
	s_nop 0
	v_cvt_pk_bf16_f32 v160, v152, v153
	v_cvt_pk_bf16_f32 v161, v154, v155
	s_movk_i32 s36, 0x400
	v_cmp_gt_u32_e32 vcc, s36, v179
	s_and_b64 exec, s[6:7], vcc
	global_store_dwordx2 v178, v[160:161], s[76:77]
	s_mov_b64 exec, -1
	s_waitcnt vmcnt(5)
	v_pk_mul_f32 v[180:181], v[180:181], v[204:205] op_sel_hi:[1,0]
	v_pk_mul_f32 v[182:183], v[182:183], v[204:205] op_sel_hi:[1,0]
	v_pk_mul_f32 v[184:185], v[184:185], v[204:205] op_sel_hi:[1,0]
	v_pk_mul_f32 v[186:187], v[186:187], v[204:205] op_sel_hi:[1,0]
	v_pk_mul_f32 v[196:197], v[196:197], v[204:205] op_sel:[0,1] op_sel_hi:[1,1]
	v_pk_mul_f32 v[198:199], v[198:199], v[204:205] op_sel:[0,1] op_sel_hi:[1,1]
	v_pk_mul_f32 v[200:201], v[200:201], v[204:205] op_sel:[0,1] op_sel_hi:[1,1]
	v_pk_mul_f32 v[202:203], v[202:203], v[204:205] op_sel:[0,1] op_sel_hi:[1,1]
	v_pk_mul_f32 v[180:181], v[208:209], v[180:181]
	v_pk_mul_f32 v[182:183], v[210:211], v[182:183]
	v_pk_mul_f32 v[184:185], v[212:213], v[184:185]
	v_pk_mul_f32 v[186:187], v[214:215], v[186:187]
	v_pk_fma_f32 v[180:181], v[216:217], v[188:189], v[180:181]
	v_pk_fma_f32 v[182:183], v[218:219], v[190:191], v[182:183]
	v_pk_fma_f32 v[184:185], v[220:221], v[192:193], v[184:185]
	v_pk_fma_f32 v[186:187], v[222:223], v[194:195], v[186:187]
	v_pk_fma_f32 v[180:181], v[224:225], v[196:197], v[180:181]
	v_pk_fma_f32 v[182:183], v[226:227], v[198:199], v[182:183]
	v_pk_fma_f32 v[184:185], v[228:229], v[200:201], v[184:185]
	v_pk_fma_f32 v[186:187], v[230:231], v[202:203], v[186:187]
	v_pk_add_f32 v[180:181], v[180:181], v[232:233]
	v_pk_add_f32 v[182:183], v[182:183], v[234:235]
	v_pk_add_f32 v[184:185], v[184:185], v[236:237]
	v_pk_add_f32 v[186:187], v[186:187], v[238:239]
	v_mul_f32_e32 v192, 0xbfb8aa3b, v184
	v_mul_f32_e32 v193, 0xbfb8aa3b, v185
	v_mul_f32_e32 v194, 0xbfb8aa3b, v186
	v_mul_f32_e32 v195, 0xbfb8aa3b, v187
	v_exp_f32_e32 v192, v192
	v_exp_f32_e32 v193, v193
	v_exp_f32_e32 v194, v194
	v_exp_f32_e32 v195, v195
	v_add_f32_e32 v192, 1.0, v192
	v_add_f32_e32 v193, 1.0, v193
	v_add_f32_e32 v194, 1.0, v194
	v_add_f32_e32 v195, 1.0, v195
	v_rcp_f32_e32 v192, v192
	v_rcp_f32_e32 v193, v193
	v_rcp_f32_e32 v194, v194
	v_rcp_f32_e32 v195, v195
	s_nop 0
	v_pk_mul_f32 v[184:185], v[184:185], v[192:193]
	v_pk_mul_f32 v[186:187], v[186:187], v[194:195]
	s_nop 0
	v_pk_mul_f32 v[180:181], v[180:181], v[184:185]
	v_pk_mul_f32 v[182:183], v[182:183], v[186:187]
	s_nop 0
	v_cvt_pk_bf16_f32 v188, v180, v181
	v_cvt_pk_bf16_f32 v189, v182, v183
	s_movk_i32 s36, 0x400
	v_cmp_gt_u32_e32 vcc, s36, v207
	s_and_b64 exec, s[6:7], vcc
	global_store_dwordx2 v206, v[188:189], s[76:77]
	s_mov_b64 exec, -1
